# S5 state-only super-tiles: 4 tiles per routine without per-tile barriers, next tile's U fragments fetched behind the MFMAs, lane exchange by DPP instead of ds_bpermute; split moved to 44/20
# speedup vs baseline: 1.0044x; 1.0044x over previous
.LBB0_827:
	s_and_b64 vcc, exec, s[0:1]
	s_cbranch_vccz .LBB0_923
	v_readlane_b32 s0, v251, 17
	s_cmpk_gt_i32 s0, 0xff
	s_cbranch_scc1 .LBB0_923
	s_lshr_b32 s101, s0, 7
	s_mul_i32 s100, s101, 20
	s_add_i32 s100, s100, 44
	s_mul_i32 s101, s101, 44
	v_readlane_b32 s0, v251, 22
	s_add_u32 s50, s0, 0x38400000
	s_movk_i32 s0, 0x400
	v_readlane_b32 s1, v251, 23
	v_cmp_gt_i32_e64 s[6:7], s0, v172
	v_readlane_b32 s0, v251, 13
	s_addc_u32 s51, s1, 0
	s_waitcnt lgkmcnt(0)
	v_lshrrev_b32_e32 v1, 4, v170
	s_andn2_b32 s0, s0, 63
	s_waitcnt vmcnt(0)
	v_bfe_u32 v110, v172, 4, 4
	v_lshlrev_b32_e32 v12, 2, v1
	s_add_i32 s0, s0, 64
	v_max_i32_e32 v39, 0x200, v172
	v_and_b32_e32 v108, 15, v172
	v_ashrrev_i32_e32 v4, 6, v172
	v_lshlrev_b32_e32 v8, 3, v110
	v_or_b32_e32 v22, s0, v12
	v_or_b32_e32 v23, 1, v12
	v_or_b32_e32 v24, 2, v12
	v_or_b32_e32 v26, 16, v12
	v_or_b32_e32 v28, 18, v12
	v_or_b32_e32 v30, 32, v12
	v_or_b32_e32 v32, 34, v12
	v_or_b32_e32 v34, 48, v12
	v_or_b32_e32 v12, 50, v12
	v_sub_u32_e32 v39, v39, v172
	v_lshlrev_b32_e32 v109, 3, v172
	v_and_b32_e32 v5, -4, v4
	v_add_u32_e32 v0, 0, v8
	v_mul_u32_u24_e32 v9, 56, v110
	v_lshlrev_b32_e32 v10, 2, v108
	v_lshlrev_b32_e32 v25, 3, v24
	v_or_b32_e32 v24, s0, v24
	v_lshlrev_b32_e32 v27, 3, v26
	v_or_b32_e32 v26, s0, v26
	v_lshlrev_b32_e32 v29, 3, v28
	v_or_b32_e32 v28, s0, v28
	v_lshlrev_b32_e32 v31, 3, v30
	v_or_b32_e32 v30, s0, v30
	v_lshlrev_b32_e32 v33, 3, v32
	v_or_b32_e32 v32, s0, v32
	v_lshlrev_b32_e32 v35, 3, v34
	v_or_b32_e32 v34, s0, v34
	v_lshlrev_b32_e32 v36, 3, v12
	v_or_b32_e32 v12, s0, v12
	v_add_u32_e32 v39, 0x1ff, v39
	s_add_i32 s0, 0, 0x10a04
	v_cmp_eq_u32_e32 vcc, 0, v5
	v_cmp_eq_u32_e64 s[8:9], v110, v108
	v_add3_u32 v111, v0, v9, v10
	v_lshrrev_b32_e32 v0, 1, v170
	v_add_u32_e32 v40, s0, v109
	s_movk_i32 s0, 0x19ff
	v_lshlrev_b32_e32 v42, 3, v39
	s_and_b64 s[56:57], vcc, s[8:9]
	v_and_b32_e32 v11, 8, v0
	v_readlane_b32 s2, v251, 26
	v_and_b32_e32 v0, 1, v172
	v_cmp_lt_u32_e32 vcc, s0, v39
	v_and_b32_e32 v42, 0xfffff000, v42
	s_brev_b32 s0, 4
	s_lshl_b32 s1, s2, 4
	v_cmp_eq_u32_e64 s[8:9], 0, v0
	v_mov_b32_e32 v0, 0x3ffffffe
	v_lshrrev_b32_e32 v41, 9, v39
	v_cmp_gt_u32_e64 s[20:21], s0, v39
	v_add_u32_e32 v39, v40, v42
	v_or_b32_e32 v13, s1, v108
	v_bitop3_b32 v0, s1, v0, v108 bitop3:0xc8
	s_movk_i32 s1, 0x440
	v_cmp_ge_u32_e64 s[22:23], v39, v40
	v_cmp_gt_i32_e64 s[10:11], s1, v172
	s_and_b64 s[0:1], s[22:23], s[20:21]
	v_or_b32_e32 v4, 3, v4
	s_and_b64 s[22:23], vcc, s[0:1]
	s_add_i32 s0, 0, 0x2000
	v_lshl_add_u32 v128, v4, 9, s0
	v_lshl_add_u32 v129, v5, 9, s0
	s_add_i32 s0, 0, 0x4000
	v_lshrrev_b32_e32 v9, 5, v170
	v_add_u32_e32 v131, s0, v8
	s_add_i32 s0, 0, 0xe800
	v_cmp_ge_i32_e64 s[12:13], s2, v9
	v_sub_u32_e32 v18, s2, v9
	v_or_b32_e32 v20, 2, v9
	v_or_b32_e32 v21, 4, v9
	v_or_b32_e32 v9, 6, v9
	v_lshl_add_u32 v132, v172, 2, s0
	v_readlane_b32 s0, v251, 24
	v_add_u32_e32 v10, 0, v10
	v_ashrrev_i32_e32 v14, 1, v13
	v_and_b32_e32 v17, 48, v172
	v_lshl_add_u32 v117, v13, 1, 0
	v_mul_u32_u24_e32 v13, 0x10c, v108
	v_cmp_ge_i32_e64 s[14:15], s2, v20
	v_sub_u32_e32 v20, s2, v20
	v_cmp_ge_i32_e64 s[16:17], s2, v21
	v_sub_u32_e32 v21, s2, v21
	v_cmp_ge_i32_e64 s[18:19], s2, v9
	v_sub_u32_e32 v9, s2, v9
	v_lshlrev_b32_e32 v96, 1, v108
	v_readlane_b32 s1, v251, 25
	s_load_dwordx2 s[52:53], s[48:49], 0x68
	s_load_dwordx2 s[54:55], s[48:49], 0x28
	s_load_dwordx8 s[24:31], s[48:49], 0x48
	v_lshlrev_b32_e32 v15, 1, v170
	v_add3_u32 v118, v10, v13, v17
	v_lshl_add_u32 v18, v18, 10, v10
	v_lshl_add_u32 v20, v20, 10, v10
	v_lshl_add_u32 v21, v21, 10, v10
	v_lshl_add_u32 v9, v9, 10, v10
	v_lshlrev_b32_e32 v10, 5, v1
	v_mul_u32_u24_e32 v124, 0x440, v1
	v_lshl_add_u64 v[98:99], s[0:1], 0, v[96:97]
	s_add_i32 s0, s2, 0x1800
	v_lshlrev_b32_e32 v1, 13, v1
	v_and_b32_e32 v15, 64, v15
	v_add_u32_e32 v134, s0, v1
	v_readlane_b32 s0, v251, 15
	v_ashrrev_i32_e32 v2, 5, v172
	v_lshl_add_u32 v37, v14, 7, 0
	v_sub_u32_e32 v14, v14, v15
	v_ashrrev_i32_e32 v15, 8, v172
	v_add_u32_e32 v173, 0x200, v172
	s_lshl_b32 s48, s0, 4
	s_add_i32 s0, s2, 0x1000
	v_and_b32_e32 v92, -2, v2
	v_lshlrev_b32_e32 v6, 9, v108
	s_add_i32 s33, 0, 0x10a00
	v_or_b32_e32 v94, 1, v2
	v_lshlrev_b32_e32 v119, 10, v5
	v_lshlrev_b32_e32 v120, 3, v15
	v_mul_i32_i24_e32 v121, 0x1100, v15
	v_ashrrev_i32_e32 v15, 8, v173
	v_add_u32_e32 v41, 1, v41
	v_add_u32_e32 v135, s0, v1
	s_add_i32 s0, s2, 0x800
	v_lshl_add_u32 v3, v170, 7, 0
	v_add_u32_e32 v7, s33, v6
	v_lshl_add_u32 v112, v0, 2, 0
	v_bfe_u32 v113, v172, 1, 3
	v_and_b32_e32 v0, 8, v109
	v_mul_u32_u24_e32 v16, 0x110, v108
	v_lshlrev_b32_e32 v13, 3, v92
	v_lshlrev_b32_e32 v2, 3, v94
	v_lshlrev_b32_e32 v19, 6, v11
	v_lshlrev_b32_e32 v22, 3, v22
	v_lshlrev_b32_e32 v24, 3, v24
	v_lshlrev_b32_e32 v26, 3, v26
	v_lshlrev_b32_e32 v28, 3, v28
	v_lshlrev_b32_e32 v30, 3, v30
	v_lshlrev_b32_e32 v32, 3, v32
	v_lshlrev_b32_e32 v34, 3, v34
	v_lshlrev_b32_e32 v12, 3, v12
	v_lshlrev_b32_e32 v11, 3, v11
	v_lshlrev_b32_e32 v14, 3, v14
	v_lshlrev_b32_e32 v122, 3, v15
	v_mul_i32_i24_e32 v123, 0x1100, v15
	v_mul_u32_u24_e32 v125, 0x110, v23
	v_or_b32_e32 v15, 0x400, v119
	v_or_b32_e32 v23, 0x800, v119
	v_lshlrev_b32_e32 v38, 10, v4
	v_and_b32_e32 v126, 0xfffffe, v41
	v_readlane_b32 s49, v251, 17
	s_and_b32 s49, s49, 0x7f
	v_add_u32_e32 v136, s0, v1
	s_add_i32 s0, 0, 0x6000
	v_cmp_lt_u32_e64 s[4:5], 63, v172
	v_mul_u32_u24_e32 v114, 0x110, v110
	v_lshlrev_b32_e32 v115, 5, v113
	v_lshlrev_b32_e32 v116, 1, v0
	v_ashrrev_i32_e32 v93, 31, v92
	v_ashrrev_i32_e32 v95, 31, v94
	v_lshl_add_u32 v127, v126, 9, v172
	v_cmp_ne_u32_e64 s[20:21], v41, v126
	v_add_u32_e32 v130, 0, v6
	v_add_u32_e32 v133, 0xfffffe00, v172
	s_lshl_b32 s35, s49, 4
	v_add_u32_e32 v137, s2, v1
	v_add3_u32 v138, v16, v17, s0
	v_add_u32_e32 v139, v3, v13
	v_add_u32_e32 v140, v3, v2
	v_add_u32_e32 v141, v111, v15
	v_add_u32_e32 v142, v111, v23
	v_add_u32_e32 v143, v111, v38
	v_add_u32_e32 v144, v7, v10
	v_add_u32_e32 v145, 0, v22
	v_add_u32_e32 v146, v7, v25
	v_add_u32_e32 v147, 0, v24
	v_add_u32_e32 v148, v7, v27
	v_add_u32_e32 v149, 0, v26
	v_add_u32_e32 v150, v7, v29
	v_add_u32_e32 v151, 0, v28
	v_add_u32_e32 v152, v7, v31
	v_add_u32_e32 v153, 0, v30
	v_add_u32_e32 v154, v7, v33
	v_add_u32_e32 v155, 0, v32
	v_add_u32_e32 v156, v7, v35
	v_add_u32_e32 v157, 0, v34
	v_add_u32_e32 v158, v7, v36
	v_add_u32_e32 v159, 0, v12
	v_add_u32_e32 v160, v37, v11
	v_add_u32_e32 v161, 0, v14
	v_lshlrev_b32_e32 v96, 1, v0
	v_add_u32_e32 v162, v18, v19
	v_add_u32_e32 v163, v20, v19
	v_add_u32_e32 v164, v21, v19
	v_add_u32_e32 v165, v9, v19
	s_branch .LBB0_831

.Ls5_state_only:
	ds_read_b128 v[174:177], v166
	ds_read_b128 v[178:181], v166 offset:64
	ds_read_b128 v[182:185], v166 offset:128
	ds_read_b128 v[186:189], v166 offset:192
	s_waitcnt lgkmcnt(3)
	v_mfma_f32_16x16x32_bf16 v[64:67], v[174:177], v[20:23], v[64:67]
	s_waitcnt lgkmcnt(1)
	v_mfma_f32_16x16x32_bf16 v[190:193], v[182:185], v[28:31], 0
	v_mfma_f32_16x16x32_bf16 v[64:67], v[178:181], v[24:27], v[64:67]
	s_waitcnt lgkmcnt(0)
	v_mfma_f32_16x16x32_bf16 v[190:193], v[186:189], v[32:35], v[190:193]
	ds_read_b128 v[174:177], v166 offset:4352
	ds_read_b128 v[178:181], v166 offset:4416
	ds_read_b128 v[182:185], v166 offset:4480
	ds_read_b128 v[186:189], v166 offset:4544
	s_nop 5
	v_pk_add_f32 v[200:201], v[64:65], v[190:191]
	v_pk_add_f32 v[198:199], v[66:67], v[192:193]
	s_nop 1
	v_mov_b32_dpp v194, v200 quad_perm:[1,0,3,2] row_mask:0xf bank_mask:0xf
	v_mov_b32_dpp v195, v201 quad_perm:[1,0,3,2] row_mask:0xf bank_mask:0xf
	v_mov_b32_dpp v196, v198 quad_perm:[1,0,3,2] row_mask:0xf bank_mask:0xf
	v_mov_b32_dpp v197, v199 quad_perm:[1,0,3,2] row_mask:0xf bank_mask:0xf
	v_pk_mul_f32 v[196:197], v[80:81], v[196:197]
	v_pk_mul_f32 v[194:195], v[68:69], v[194:195]
	s_nop 0
	v_pk_fma_f32 v[66:67], v[78:79], v[198:199], v[196:197]
	v_pk_fma_f32 v[64:65], v[100:101], v[200:201], v[194:195]
	s_nop 2
	s_waitcnt lgkmcnt(3)
	v_mfma_f32_16x16x32_bf16 v[64:67], v[174:177], v[20:23], v[64:67]
	s_waitcnt lgkmcnt(1)
	v_mfma_f32_16x16x32_bf16 v[190:193], v[182:185], v[28:31], 0
	v_mfma_f32_16x16x32_bf16 v[64:67], v[178:181], v[24:27], v[64:67]
	s_waitcnt lgkmcnt(0)
	v_mfma_f32_16x16x32_bf16 v[190:193], v[186:189], v[32:35], v[190:193]
	ds_read_b128 v[174:177], v166 offset:8704
	ds_read_b128 v[178:181], v166 offset:8768
	ds_read_b128 v[182:185], v166 offset:8832
	ds_read_b128 v[186:189], v166 offset:8896
	s_nop 5
	v_pk_add_f32 v[200:201], v[64:65], v[190:191]
	v_pk_add_f32 v[198:199], v[66:67], v[192:193]
	s_nop 1
	v_mov_b32_dpp v194, v200 quad_perm:[1,0,3,2] row_mask:0xf bank_mask:0xf
	v_mov_b32_dpp v195, v201 quad_perm:[1,0,3,2] row_mask:0xf bank_mask:0xf
	v_mov_b32_dpp v196, v198 quad_perm:[1,0,3,2] row_mask:0xf bank_mask:0xf
	v_mov_b32_dpp v197, v199 quad_perm:[1,0,3,2] row_mask:0xf bank_mask:0xf
	v_pk_mul_f32 v[196:197], v[80:81], v[196:197]
	v_pk_mul_f32 v[194:195], v[68:69], v[194:195]
	s_nop 0
	v_pk_fma_f32 v[66:67], v[78:79], v[198:199], v[196:197]
	v_pk_fma_f32 v[64:65], v[100:101], v[200:201], v[194:195]
	s_nop 2
	s_waitcnt lgkmcnt(3)
	v_mfma_f32_16x16x32_bf16 v[64:67], v[174:177], v[20:23], v[64:67]
	s_waitcnt lgkmcnt(1)
	v_mfma_f32_16x16x32_bf16 v[190:193], v[182:185], v[28:31], 0
	v_mfma_f32_16x16x32_bf16 v[64:67], v[178:181], v[24:27], v[64:67]
	s_waitcnt lgkmcnt(0)
	v_mfma_f32_16x16x32_bf16 v[190:193], v[186:189], v[32:35], v[190:193]
	ds_read_b128 v[174:177], v166 offset:13056
	ds_read_b128 v[178:181], v166 offset:13120
	ds_read_b128 v[182:185], v166 offset:13184
	ds_read_b128 v[186:189], v166 offset:13248
	s_nop 5
	v_pk_add_f32 v[200:201], v[64:65], v[190:191]
	v_pk_add_f32 v[198:199], v[66:67], v[192:193]
	s_nop 1
	v_mov_b32_dpp v194, v200 quad_perm:[1,0,3,2] row_mask:0xf bank_mask:0xf
	v_mov_b32_dpp v195, v201 quad_perm:[1,0,3,2] row_mask:0xf bank_mask:0xf
	v_mov_b32_dpp v196, v198 quad_perm:[1,0,3,2] row_mask:0xf bank_mask:0xf
	v_mov_b32_dpp v197, v199 quad_perm:[1,0,3,2] row_mask:0xf bank_mask:0xf
	v_pk_mul_f32 v[196:197], v[80:81], v[196:197]
	v_pk_mul_f32 v[194:195], v[68:69], v[194:195]
	s_nop 0
	v_pk_fma_f32 v[66:67], v[78:79], v[198:199], v[196:197]
	v_pk_fma_f32 v[64:65], v[100:101], v[200:201], v[194:195]
	s_nop 2
	s_waitcnt lgkmcnt(3)
	v_mfma_f32_16x16x32_bf16 v[64:67], v[174:177], v[20:23], v[64:67]
	s_waitcnt lgkmcnt(1)
	v_mfma_f32_16x16x32_bf16 v[190:193], v[182:185], v[28:31], 0
	v_mfma_f32_16x16x32_bf16 v[64:67], v[178:181], v[24:27], v[64:67]
	s_waitcnt lgkmcnt(0)
	v_mfma_f32_16x16x32_bf16 v[190:193], v[186:189], v[32:35], v[190:193]
	s_nop 7
	s_nop 1
	v_pk_add_f32 v[200:201], v[64:65], v[190:191]
	v_pk_add_f32 v[198:199], v[66:67], v[192:193]
	s_nop 1
	v_mov_b32_dpp v194, v200 quad_perm:[1,0,3,2] row_mask:0xf bank_mask:0xf
	v_mov_b32_dpp v195, v201 quad_perm:[1,0,3,2] row_mask:0xf bank_mask:0xf
	v_mov_b32_dpp v196, v198 quad_perm:[1,0,3,2] row_mask:0xf bank_mask:0xf
	v_mov_b32_dpp v197, v199 quad_perm:[1,0,3,2] row_mask:0xf bank_mask:0xf
	v_cvt_pk_bf16_f32 v65, v200, s0
	v_add_u32_e32 v66, v117, v124
	ds_write_b16 v66, v65 offset:59392
	v_cvt_pk_bf16_f32 v65, v201, s0
	v_add_u32_e32 v64, v117, v125
	ds_write_b16 v64, v65 offset:59392
	v_cvt_pk_bf16_f32 v65, v198, s0
	ds_write_b16 v64, v65 offset:59664
	v_cvt_pk_bf16_f32 v65, v199, s0
	ds_write_b16 v64, v65 offset:59936
	v_pk_mul_f32 v[196:197], v[80:81], v[196:197]
	v_pk_mul_f32 v[194:195], v[68:69], v[194:195]
	s_nop 0
	v_pk_fma_f32 v[66:67], v[78:79], v[198:199], v[196:197]
	v_pk_fma_f32 v[64:65], v[100:101], v[200:201], v[194:195]
	s_nop 2
	s_mov_b64 s[2:3], 0x10000
	s_branch .LBB0_917

